# P3L: P3 final epilogue issues all 16 gate-vector loads up front (was one in flight at a time)
# baseline (speedup 1.0000x reference)
; __device__ __forceinline__ u32x4 pack8(f32x4 a, f32x4 b) { u32x4 w; w.x = cvt_pk_bf16(a[0], a[1]); w.y = cvt_pk_bf16(a[2], a[3]); w.z = cvt_pk_bf16(b[0], b[1]); w.w = cvt_pk_bf16(b[2], b[3]); return w; }
; #define EPI_LOOP(...) _Pragma("unroll") for (int ai = 0; ai < 2; ++ai) _Pragma("unroll") for (int m = 0; m < 4; ++m) { const int row = u.pm * 256 + ai * 128 + wr * 64 + m * 16 + fr; \
;     _Pragma("unroll") for (int bj = 0; bj < 2; ++bj) { const int tc = bj * 128 + wc * 32 + 8 * fq; f32x4 v0 = acc[ai][bj][m][0], v1 = acc[ai][bj][m][1]; __VA_ARGS__ } }
;     __device__ __forceinline__ void operator()(const f32x4 (&acc)[2][2][4][2], const pg8::Unit& u, int wr, int wc, int fr, int fq) const {
;         EPI_LOOP({ const int col = u.pn * 256 + tc; f32x4 a0, a1; unpack_bf16x8(*(const u32x4*)(G + (size_t)row * 2048 + 1024 + col), a0, a1);
;                    _Pragma("unroll") for (int i = 0; i < 4; ++i) { a0[i] = fmaxf(a0[i], 1e-30f); a1[i] = fmaxf(a1[i], 1e-30f); }
;                    *(u32x4*)(MIXED + (size_t)row * D + col) = pack8(v0 * a0, v1 * a1); })
;     }
.LBB0_671:
	v_mov_b64_e32 v[248:249], v[156:157]
	s_mov_b64 s[96:97], 0x10000
	s_mov_b64 s[98:99], 0x50000
	global_load_dwordx4 v[184:187], v[248:249], off offset:2048
	global_load_dwordx4 v[188:191], v[248:249], off offset:2304
	v_lshl_add_u64 v[248:249], v[248:249], 0, s[96:97]
	global_load_dwordx4 v[192:195], v[248:249], off offset:2048
	global_load_dwordx4 v[196:199], v[248:249], off offset:2304
	v_lshl_add_u64 v[248:249], v[248:249], 0, s[96:97]
	global_load_dwordx4 v[200:203], v[248:249], off offset:2048
	global_load_dwordx4 v[204:207], v[248:249], off offset:2304
	v_lshl_add_u64 v[248:249], v[248:249], 0, s[96:97]
	global_load_dwordx4 v[208:211], v[248:249], off offset:2048
	global_load_dwordx4 v[212:215], v[248:249], off offset:2304
	v_lshl_add_u64 v[248:249], v[248:249], 0, s[98:99]
	global_load_dwordx4 v[216:219], v[248:249], off offset:2048
	global_load_dwordx4 v[220:223], v[248:249], off offset:2304
	v_lshl_add_u64 v[248:249], v[248:249], 0, s[96:97]
	global_load_dwordx4 v[224:227], v[248:249], off offset:2048
	global_load_dwordx4 v[228:231], v[248:249], off offset:2304
	v_lshl_add_u64 v[248:249], v[248:249], 0, s[96:97]
	global_load_dwordx4 v[232:235], v[248:249], off offset:2048
	global_load_dwordx4 v[236:239], v[248:249], off offset:2304
	v_lshl_add_u64 v[248:249], v[248:249], 0, s[96:97]
	global_load_dwordx4 v[240:243], v[248:249], off offset:2048
	global_load_dwordx4 v[244:247], v[248:249], off offset:2304
	s_andn2_b64 vcc, exec, s[2:3]
	s_mov_b64 s[2:3], -1
	s_waitcnt vmcnt(15)
	v_lshlrev_b32_e32 v158, 16, v184
	v_and_b32_e32 v128, 0xffff0000, v184
	v_lshlrev_b32_e32 v159, 16, v185
	v_and_b32_e32 v129, 0xffff0000, v185
	v_lshlrev_b32_e32 v160, 16, v186
	v_and_b32_e32 v130, 0xffff0000, v186
	v_lshlrev_b32_e32 v161, 16, v187
	v_and_b32_e32 v131, 0xffff0000, v187
	v_max_f32_e32 v158, v158, v158
	v_max_f32_e32 v160, v160, v160
	v_max_f32_e32 v162, v128, v128
	v_max_f32_e32 v163, v130, v130
	v_max_f32_e32 v159, v159, v159
	v_max_f32_e32 v161, v161, v161
	v_max_f32_e32 v164, v129, v129
	v_max_f32_e32 v165, v131, v131
	v_max_f32_e32 v128, 0xda24260, v158
	v_max_f32_e32 v130, 0xda24260, v160
	v_max_f32_e32 v129, 0xda24260, v162
	v_max_f32_e32 v131, 0xda24260, v163
	v_max_f32_e32 v158, 0xda24260, v159
	v_max_f32_e32 v160, 0xda24260, v161
	v_max_f32_e32 v159, 0xda24260, v164
	v_max_f32_e32 v161, 0xda24260, v165
	v_pk_mul_f32 v[126:127], v[126:127], v[158:159]
	v_pk_mul_f32 v[124:125], v[124:125], v[128:129]
	v_pk_mul_f32 v[128:129], v[122:123], v[160:161]
	v_pk_mul_f32 v[122:123], v[120:121], v[130:131]
	v_cvt_pk_bf16_f32 v120, v124, v125
	v_cvt_pk_bf16_f32 v121, v126, v127
	v_add_u32_e32 v130, 16, v154
	v_cvt_pk_bf16_f32 v122, v122, v123
	v_cvt_pk_bf16_f32 v123, v128, v129
	s_nop 0
	v_lshlrev_b64 v[128:129], 11, v[154:155]
	v_lshl_add_u64 v[128:129], s[6:7], 0, v[128:129]
	v_lshl_add_u64 v[128:129], v[128:129], 0, v[152:153]
	v_ashrrev_i32_e32 v131, 31, v130
	global_store_dwordx4 v[128:129], v[120:123], off
	v_lshlrev_b64 v[156:157], 12, v[130:131]
	v_lshl_add_u64 v[156:157], s[4:5], 0, v[156:157]
	v_lshl_add_u64 v[156:157], v[156:157], 0, v[152:153]
	s_waitcnt vmcnt(15)
	v_lshlrev_b32_e32 v120, 16, v188
	v_and_b32_e32 v121, 0xffff0000, v188
	v_lshlrev_b32_e32 v122, 16, v189
	v_and_b32_e32 v123, 0xffff0000, v189
	v_lshlrev_b32_e32 v124, 16, v190
	v_and_b32_e32 v125, 0xffff0000, v190
	v_lshlrev_b32_e32 v126, 16, v191
	v_and_b32_e32 v127, 0xffff0000, v191
	v_max_f32_e32 v120, v120, v120
	v_max_f32_e32 v124, v124, v124
	v_max_f32_e32 v121, v121, v121
	v_max_f32_e32 v125, v125, v125
	v_max_f32_e32 v155, v122, v122
	v_max_f32_e32 v126, v126, v126
	v_max_f32_e32 v158, v123, v123
	v_max_f32_e32 v127, v127, v127
	v_max_f32_e32 v120, 0xda24260, v120
	v_max_f32_e32 v122, 0xda24260, v124
	v_max_f32_e32 v121, 0xda24260, v121
	v_max_f32_e32 v123, 0xda24260, v125
	v_max_f32_e32 v124, 0xda24260, v155
	v_max_f32_e32 v126, 0xda24260, v126
	v_max_f32_e32 v125, 0xda24260, v158
	v_max_f32_e32 v127, 0xda24260, v127
	v_pk_mul_f32 v[118:119], v[118:119], v[124:125]
	v_pk_mul_f32 v[116:117], v[116:117], v[120:121]
	v_pk_mul_f32 v[120:121], v[114:115], v[126:127]
	v_pk_mul_f32 v[114:115], v[112:113], v[122:123]
	v_cvt_pk_bf16_f32 v112, v116, v117
	v_cvt_pk_bf16_f32 v113, v118, v119
	s_nop 0
	v_cvt_pk_bf16_f32 v114, v114, v115
	v_cvt_pk_bf16_f32 v115, v120, v121
	s_nop 0
	s_nop 0
	global_store_dwordx4 v[128:129], v[112:115], off offset:256
	s_waitcnt vmcnt(15)
	s_nop 0
	v_lshlrev_b32_e32 v112, 16, v192
	v_and_b32_e32 v113, 0xffff0000, v192
	v_lshlrev_b32_e32 v114, 16, v193
	v_and_b32_e32 v115, 0xffff0000, v193
	v_lshlrev_b32_e32 v116, 16, v194
	v_and_b32_e32 v117, 0xffff0000, v194
	v_lshlrev_b32_e32 v118, 16, v195
	v_and_b32_e32 v119, 0xffff0000, v195
	v_max_f32_e32 v112, v112, v112
	v_max_f32_e32 v116, v116, v116
	v_max_f32_e32 v113, v113, v113
	v_max_f32_e32 v117, v117, v117
	v_max_f32_e32 v120, v114, v114
	v_max_f32_e32 v118, v118, v118
	v_max_f32_e32 v121, v115, v115
	v_max_f32_e32 v119, v119, v119
	v_max_f32_e32 v112, 0xda24260, v112
	v_max_f32_e32 v114, 0xda24260, v116
	v_max_f32_e32 v113, 0xda24260, v113
	v_max_f32_e32 v115, 0xda24260, v117
	v_max_f32_e32 v116, 0xda24260, v120
	v_max_f32_e32 v118, 0xda24260, v118
	v_max_f32_e32 v117, 0xda24260, v121
	v_max_f32_e32 v119, 0xda24260, v119
	v_pk_mul_f32 v[110:111], v[110:111], v[116:117]
	v_pk_mul_f32 v[108:109], v[108:109], v[112:113]
	v_pk_mul_f32 v[112:113], v[106:107], v[118:119]
	v_pk_mul_f32 v[106:107], v[104:105], v[114:115]
	v_cvt_pk_bf16_f32 v104, v108, v109
	v_cvt_pk_bf16_f32 v105, v110, v111
	v_lshlrev_b64 v[114:115], 11, v[130:131]
	v_cvt_pk_bf16_f32 v106, v106, v107
	v_cvt_pk_bf16_f32 v107, v112, v113
	s_nop 0
	v_lshl_add_u64 v[114:115], s[6:7], 0, v[114:115]
	v_add_u32_e32 v112, 32, v154
	v_lshl_add_u64 v[114:115], v[114:115], 0, v[152:153]
	v_ashrrev_i32_e32 v113, 31, v112
	global_store_dwordx4 v[114:115], v[104:107], off
	v_lshlrev_b64 v[116:117], 12, v[112:113]
	v_lshl_add_u64 v[116:117], s[4:5], 0, v[116:117]
	v_lshl_add_u64 v[116:117], v[116:117], 0, v[152:153]
	s_waitcnt vmcnt(15)
; __device__ __forceinline__ u32x4 pack8(f32x4 a, f32x4 b) { u32x4 w; w.x = cvt_pk_bf16(a[0], a[1]); w.y = cvt_pk_bf16(a[2], a[3]); w.z = cvt_pk_bf16(b[0], b[1]); w.w = cvt_pk_bf16(b[2], b[3]); return w; }
; #define EPI_LOOP(...) _Pragma("unroll") for (int ai = 0; ai < 2; ++ai) _Pragma("unroll") for (int m = 0; m < 4; ++m) { const int row = u.pm * 256 + ai * 128 + wr * 64 + m * 16 + fr; \
;     _Pragma("unroll") for (int bj = 0; bj < 2; ++bj) { const int tc = bj * 128 + wc * 32 + 8 * fq; f32x4 v0 = acc[ai][bj][m][0], v1 = acc[ai][bj][m][1]; __VA_ARGS__ } }
;     __device__ __forceinline__ void operator()(const f32x4 (&acc)[2][2][4][2], const pg8::Unit& u, int wr, int wc, int fr, int fq) const {
;         EPI_LOOP({ const int col = u.pn * 256 + tc; f32x4 a0, a1; unpack_bf16x8(*(const u32x4*)(G + (size_t)row * 2048 + 1024 + col), a0, a1);
;                    _Pragma("unroll") for (int i = 0; i < 4; ++i) { a0[i] = fmaxf(a0[i], 1e-30f); a1[i] = fmaxf(a1[i], 1e-30f); }
;                    *(u32x4*)(MIXED + (size_t)row * D + col) = pack8(v0 * a0, v1 * a1); })
;     }
	v_lshlrev_b32_e32 v104, 16, v196
	v_and_b32_e32 v105, 0xffff0000, v196
	v_lshlrev_b32_e32 v106, 16, v197
	v_and_b32_e32 v107, 0xffff0000, v197
	v_lshlrev_b32_e32 v108, 16, v198
	v_and_b32_e32 v109, 0xffff0000, v198
	v_lshlrev_b32_e32 v110, 16, v199
	v_and_b32_e32 v111, 0xffff0000, v199
	v_max_f32_e32 v104, v104, v104
	v_max_f32_e32 v108, v108, v108
	v_max_f32_e32 v105, v105, v105
	v_max_f32_e32 v109, v109, v109
	v_max_f32_e32 v118, v106, v106
	v_max_f32_e32 v110, v110, v110
	v_max_f32_e32 v119, v107, v107
	v_max_f32_e32 v111, v111, v111
	v_max_f32_e32 v104, 0xda24260, v104
	v_max_f32_e32 v106, 0xda24260, v108
	v_max_f32_e32 v105, 0xda24260, v105
	v_max_f32_e32 v107, 0xda24260, v109
	v_max_f32_e32 v108, 0xda24260, v118
	v_max_f32_e32 v110, 0xda24260, v110
	v_max_f32_e32 v109, 0xda24260, v119
	v_max_f32_e32 v111, 0xda24260, v111
	v_pk_mul_f32 v[102:103], v[102:103], v[108:109]
	v_pk_mul_f32 v[100:101], v[100:101], v[104:105]
	v_pk_mul_f32 v[104:105], v[98:99], v[110:111]
	v_pk_mul_f32 v[98:99], v[96:97], v[106:107]
	v_cvt_pk_bf16_f32 v96, v100, v101
	v_cvt_pk_bf16_f32 v97, v102, v103
	s_nop 0
	v_cvt_pk_bf16_f32 v98, v98, v99
	v_cvt_pk_bf16_f32 v99, v104, v105
	s_nop 0
	s_nop 0
	global_store_dwordx4 v[114:115], v[96:99], off offset:256
	s_waitcnt vmcnt(15)
	s_nop 0
	v_lshlrev_b32_e32 v96, 16, v200
	v_and_b32_e32 v97, 0xffff0000, v200
	v_lshlrev_b32_e32 v98, 16, v201
	v_and_b32_e32 v99, 0xffff0000, v201
	v_lshlrev_b32_e32 v100, 16, v202
	v_and_b32_e32 v101, 0xffff0000, v202
	v_lshlrev_b32_e32 v102, 16, v203
	v_and_b32_e32 v103, 0xffff0000, v203
	v_max_f32_e32 v96, v96, v96
	v_max_f32_e32 v100, v100, v100
	v_max_f32_e32 v97, v97, v97
	v_max_f32_e32 v101, v101, v101
	v_max_f32_e32 v104, v98, v98
	v_max_f32_e32 v102, v102, v102
	v_max_f32_e32 v105, v99, v99
	v_max_f32_e32 v103, v103, v103
	v_max_f32_e32 v96, 0xda24260, v96
	v_max_f32_e32 v98, 0xda24260, v100
	v_max_f32_e32 v97, 0xda24260, v97
	v_max_f32_e32 v99, 0xda24260, v101
	v_max_f32_e32 v100, 0xda24260, v104
	v_max_f32_e32 v102, 0xda24260, v102
	v_max_f32_e32 v101, 0xda24260, v105
	v_max_f32_e32 v103, 0xda24260, v103
	v_pk_mul_f32 v[94:95], v[94:95], v[100:101]
	v_pk_mul_f32 v[92:93], v[92:93], v[96:97]
	v_pk_mul_f32 v[96:97], v[90:91], v[102:103]
	v_pk_mul_f32 v[90:91], v[88:89], v[98:99]
	v_cvt_pk_bf16_f32 v88, v92, v93
	v_cvt_pk_bf16_f32 v89, v94, v95
	v_lshlrev_b64 v[98:99], 11, v[112:113]
	v_cvt_pk_bf16_f32 v90, v90, v91
	v_cvt_pk_bf16_f32 v91, v96, v97
	s_nop 0
	v_lshl_add_u64 v[98:99], s[6:7], 0, v[98:99]
	v_add_u32_e32 v96, 48, v154
	v_lshl_add_u64 v[98:99], v[98:99], 0, v[152:153]
	v_ashrrev_i32_e32 v97, 31, v96
	global_store_dwordx4 v[98:99], v[88:91], off
	v_lshlrev_b64 v[100:101], 12, v[96:97]
	v_lshl_add_u64 v[100:101], s[4:5], 0, v[100:101]
	v_lshl_add_u64 v[100:101], v[100:101], 0, v[152:153]
	s_waitcnt vmcnt(15)
	v_lshlrev_b32_e32 v88, 16, v204
	v_and_b32_e32 v89, 0xffff0000, v204
	v_lshlrev_b32_e32 v90, 16, v205
	v_and_b32_e32 v91, 0xffff0000, v205
	v_lshlrev_b32_e32 v92, 16, v206
	v_and_b32_e32 v93, 0xffff0000, v206
	v_lshlrev_b32_e32 v94, 16, v207
	v_and_b32_e32 v95, 0xffff0000, v207
	v_max_f32_e32 v88, v88, v88
	v_max_f32_e32 v92, v92, v92
	v_max_f32_e32 v89, v89, v89
	v_max_f32_e32 v93, v93, v93
	v_max_f32_e32 v102, v90, v90
	v_max_f32_e32 v94, v94, v94
	v_max_f32_e32 v103, v91, v91
	v_max_f32_e32 v95, v95, v95
	v_max_f32_e32 v88, 0xda24260, v88
	v_max_f32_e32 v90, 0xda24260, v92
	v_max_f32_e32 v89, 0xda24260, v89
	v_max_f32_e32 v91, 0xda24260, v93
	v_max_f32_e32 v92, 0xda24260, v102
	v_max_f32_e32 v94, 0xda24260, v94
	v_max_f32_e32 v93, 0xda24260, v103
	v_max_f32_e32 v95, 0xda24260, v95
	v_pk_mul_f32 v[86:87], v[86:87], v[92:93]
	v_pk_mul_f32 v[84:85], v[84:85], v[88:89]
	v_pk_mul_f32 v[88:89], v[82:83], v[94:95]
	v_pk_mul_f32 v[82:83], v[80:81], v[90:91]
	v_cvt_pk_bf16_f32 v80, v84, v85
	v_cvt_pk_bf16_f32 v81, v86, v87
	s_nop 0
	v_cvt_pk_bf16_f32 v82, v82, v83
	v_cvt_pk_bf16_f32 v83, v88, v89
	s_nop 0
	s_nop 0
	global_store_dwordx4 v[98:99], v[80:83], off offset:256
	s_waitcnt vmcnt(15)
	s_nop 0
	v_lshlrev_b32_e32 v80, 16, v208
	v_and_b32_e32 v81, 0xffff0000, v208
	v_lshlrev_b32_e32 v82, 16, v209
	v_and_b32_e32 v83, 0xffff0000, v209
	v_lshlrev_b32_e32 v84, 16, v210
	v_and_b32_e32 v85, 0xffff0000, v210
	v_lshlrev_b32_e32 v86, 16, v211
	v_and_b32_e32 v87, 0xffff0000, v211
	v_max_f32_e32 v80, v80, v80
	v_max_f32_e32 v84, v84, v84
	v_max_f32_e32 v81, v81, v81
	v_max_f32_e32 v85, v85, v85
	v_max_f32_e32 v88, v82, v82
	v_max_f32_e32 v86, v86, v86
	v_max_f32_e32 v89, v83, v83
	v_max_f32_e32 v87, v87, v87
	v_max_f32_e32 v80, 0xda24260, v80
	v_max_f32_e32 v82, 0xda24260, v84
	v_max_f32_e32 v81, 0xda24260, v81
	v_max_f32_e32 v83, 0xda24260, v85
	v_max_f32_e32 v84, 0xda24260, v88
	v_max_f32_e32 v86, 0xda24260, v86
	v_max_f32_e32 v85, 0xda24260, v89
	v_max_f32_e32 v87, 0xda24260, v87
	v_pk_mul_f32 v[78:79], v[78:79], v[84:85]
	v_pk_mul_f32 v[76:77], v[76:77], v[80:81]
	v_pk_mul_f32 v[80:81], v[74:75], v[86:87]
	v_pk_mul_f32 v[74:75], v[72:73], v[82:83]
	v_cvt_pk_bf16_f32 v72, v76, v77
	v_cvt_pk_bf16_f32 v73, v78, v79
	v_lshlrev_b64 v[82:83], 11, v[96:97]
	v_cvt_pk_bf16_f32 v74, v74, v75
	v_cvt_pk_bf16_f32 v75, v80, v81
	s_nop 0
	v_lshl_add_u64 v[82:83], s[6:7], 0, v[82:83]
	v_add_u32_e32 v80, 0x80, v154
	v_lshl_add_u64 v[82:83], v[82:83], 0, v[152:153]
	v_ashrrev_i32_e32 v81, 31, v80
	global_store_dwordx4 v[82:83], v[72:75], off
	v_lshlrev_b64 v[84:85], 12, v[80:81]
	v_lshl_add_u64 v[84:85], s[4:5], 0, v[84:85]
	v_lshl_add_u64 v[84:85], v[84:85], 0, v[152:153]
	s_waitcnt vmcnt(15)
; __device__ __forceinline__ u32x4 pack8(f32x4 a, f32x4 b) { u32x4 w; w.x = cvt_pk_bf16(a[0], a[1]); w.y = cvt_pk_bf16(a[2], a[3]); w.z = cvt_pk_bf16(b[0], b[1]); w.w = cvt_pk_bf16(b[2], b[3]); return w; }
; #define EPI_LOOP(...) _Pragma("unroll") for (int ai = 0; ai < 2; ++ai) _Pragma("unroll") for (int m = 0; m < 4; ++m) { const int row = u.pm * 256 + ai * 128 + wr * 64 + m * 16 + fr; \
;     _Pragma("unroll") for (int bj = 0; bj < 2; ++bj) { const int tc = bj * 128 + wc * 32 + 8 * fq; f32x4 v0 = acc[ai][bj][m][0], v1 = acc[ai][bj][m][1]; __VA_ARGS__ } }
;     __device__ __forceinline__ void operator()(const f32x4 (&acc)[2][2][4][2], const pg8::Unit& u, int wr, int wc, int fr, int fq) const {
;         EPI_LOOP({ const int col = u.pn * 256 + tc; f32x4 a0, a1; unpack_bf16x8(*(const u32x4*)(G + (size_t)row * 2048 + 1024 + col), a0, a1);
;                    _Pragma("unroll") for (int i = 0; i < 4; ++i) { a0[i] = fmaxf(a0[i], 1e-30f); a1[i] = fmaxf(a1[i], 1e-30f); }
;                    *(u32x4*)(MIXED + (size_t)row * D + col) = pack8(v0 * a0, v1 * a1); })
;     }
	v_lshlrev_b32_e32 v72, 16, v212
	v_and_b32_e32 v73, 0xffff0000, v212
	v_lshlrev_b32_e32 v74, 16, v213
	v_and_b32_e32 v75, 0xffff0000, v213
	v_lshlrev_b32_e32 v76, 16, v214
	v_and_b32_e32 v77, 0xffff0000, v214
	v_lshlrev_b32_e32 v78, 16, v215
	v_and_b32_e32 v79, 0xffff0000, v215
	v_max_f32_e32 v72, v72, v72
	v_max_f32_e32 v76, v76, v76
	v_max_f32_e32 v73, v73, v73
	v_max_f32_e32 v77, v77, v77
	v_max_f32_e32 v86, v74, v74
	v_max_f32_e32 v78, v78, v78
	v_max_f32_e32 v87, v75, v75
	v_max_f32_e32 v79, v79, v79
	v_max_f32_e32 v72, 0xda24260, v72
	v_max_f32_e32 v74, 0xda24260, v76
	v_max_f32_e32 v73, 0xda24260, v73
	v_max_f32_e32 v75, 0xda24260, v77
	v_max_f32_e32 v76, 0xda24260, v86
	v_max_f32_e32 v78, 0xda24260, v78
	v_max_f32_e32 v77, 0xda24260, v87
	v_max_f32_e32 v79, 0xda24260, v79
	v_pk_mul_f32 v[70:71], v[70:71], v[76:77]
	v_pk_mul_f32 v[68:69], v[68:69], v[72:73]
	v_pk_mul_f32 v[72:73], v[66:67], v[78:79]
	v_pk_mul_f32 v[66:67], v[64:65], v[74:75]
	v_cvt_pk_bf16_f32 v64, v68, v69
	v_cvt_pk_bf16_f32 v65, v70, v71
	s_nop 0
	v_cvt_pk_bf16_f32 v66, v66, v67
	v_cvt_pk_bf16_f32 v67, v72, v73
	s_nop 0
	s_nop 0
	global_store_dwordx4 v[82:83], v[64:67], off offset:256
	s_waitcnt vmcnt(15)
	s_nop 0
	v_lshlrev_b32_e32 v64, 16, v216
	v_and_b32_e32 v65, 0xffff0000, v216
	v_lshlrev_b32_e32 v66, 16, v217
	v_and_b32_e32 v67, 0xffff0000, v217
	v_lshlrev_b32_e32 v68, 16, v218
	v_and_b32_e32 v69, 0xffff0000, v218
	v_lshlrev_b32_e32 v70, 16, v219
	v_and_b32_e32 v71, 0xffff0000, v219
	v_max_f32_e32 v64, v64, v64
	v_max_f32_e32 v68, v68, v68
	v_max_f32_e32 v65, v65, v65
	v_max_f32_e32 v69, v69, v69
	v_max_f32_e32 v72, v66, v66
	v_max_f32_e32 v70, v70, v70
	v_max_f32_e32 v73, v67, v67
	v_max_f32_e32 v71, v71, v71
	v_max_f32_e32 v64, 0xda24260, v64
	v_max_f32_e32 v66, 0xda24260, v68
	v_max_f32_e32 v65, 0xda24260, v65
	v_max_f32_e32 v67, 0xda24260, v69
	v_max_f32_e32 v68, 0xda24260, v72
	v_max_f32_e32 v70, 0xda24260, v70
	v_max_f32_e32 v69, 0xda24260, v73
	v_max_f32_e32 v71, 0xda24260, v71
	v_pk_mul_f32 v[62:63], v[62:63], v[68:69]
	v_pk_mul_f32 v[60:61], v[60:61], v[64:65]
	v_pk_mul_f32 v[64:65], v[58:59], v[70:71]
	v_pk_mul_f32 v[58:59], v[56:57], v[66:67]
	v_cvt_pk_bf16_f32 v56, v60, v61
	v_cvt_pk_bf16_f32 v57, v62, v63
	v_lshlrev_b64 v[66:67], 11, v[80:81]
	v_cvt_pk_bf16_f32 v58, v58, v59
	v_cvt_pk_bf16_f32 v59, v64, v65
	s_nop 0
	v_lshl_add_u64 v[66:67], s[6:7], 0, v[66:67]
	v_add_u32_e32 v64, 0x90, v154
	v_lshl_add_u64 v[66:67], v[66:67], 0, v[152:153]
	v_ashrrev_i32_e32 v65, 31, v64
	global_store_dwordx4 v[66:67], v[56:59], off
	v_lshlrev_b64 v[68:69], 12, v[64:65]
	v_lshl_add_u64 v[68:69], s[4:5], 0, v[68:69]
	v_lshl_add_u64 v[68:69], v[68:69], 0, v[152:153]
	s_waitcnt vmcnt(15)
	v_lshlrev_b32_e32 v56, 16, v220
	v_and_b32_e32 v57, 0xffff0000, v220
	v_lshlrev_b32_e32 v58, 16, v221
	v_and_b32_e32 v59, 0xffff0000, v221
	v_lshlrev_b32_e32 v60, 16, v222
	v_and_b32_e32 v61, 0xffff0000, v222
	v_lshlrev_b32_e32 v62, 16, v223
	v_and_b32_e32 v63, 0xffff0000, v223
	v_max_f32_e32 v56, v56, v56
	v_max_f32_e32 v60, v60, v60
	v_max_f32_e32 v57, v57, v57
	v_max_f32_e32 v61, v61, v61
	v_max_f32_e32 v70, v58, v58
	v_max_f32_e32 v62, v62, v62
	v_max_f32_e32 v71, v59, v59
	v_max_f32_e32 v63, v63, v63
	v_max_f32_e32 v56, 0xda24260, v56
	v_max_f32_e32 v58, 0xda24260, v60
	v_max_f32_e32 v57, 0xda24260, v57
	v_max_f32_e32 v59, 0xda24260, v61
	v_max_f32_e32 v60, 0xda24260, v70
	v_max_f32_e32 v62, 0xda24260, v62
	v_max_f32_e32 v61, 0xda24260, v71
	v_max_f32_e32 v63, 0xda24260, v63
	v_pk_mul_f32 v[54:55], v[54:55], v[60:61]
	v_pk_mul_f32 v[52:53], v[52:53], v[56:57]
	v_pk_mul_f32 v[56:57], v[50:51], v[62:63]
	v_pk_mul_f32 v[50:51], v[48:49], v[58:59]
	v_cvt_pk_bf16_f32 v48, v52, v53
	v_cvt_pk_bf16_f32 v49, v54, v55
	s_nop 0
	v_cvt_pk_bf16_f32 v50, v50, v51
	v_cvt_pk_bf16_f32 v51, v56, v57
	s_nop 0
	s_nop 0
	global_store_dwordx4 v[66:67], v[48:51], off offset:256
	s_waitcnt vmcnt(15)
	s_nop 0
	v_lshlrev_b32_e32 v48, 16, v224
	v_and_b32_e32 v49, 0xffff0000, v224
	v_lshlrev_b32_e32 v50, 16, v225
	v_and_b32_e32 v51, 0xffff0000, v225
	v_lshlrev_b32_e32 v52, 16, v226
	v_and_b32_e32 v53, 0xffff0000, v226
	v_lshlrev_b32_e32 v54, 16, v227
	v_and_b32_e32 v55, 0xffff0000, v227
	v_max_f32_e32 v48, v48, v48
	v_max_f32_e32 v52, v52, v52
	v_max_f32_e32 v49, v49, v49
	v_max_f32_e32 v53, v53, v53
	v_max_f32_e32 v56, v50, v50
	v_max_f32_e32 v54, v54, v54
	v_max_f32_e32 v57, v51, v51
	v_max_f32_e32 v55, v55, v55
	v_max_f32_e32 v48, 0xda24260, v48
	v_max_f32_e32 v50, 0xda24260, v52
	v_max_f32_e32 v49, 0xda24260, v49
	v_max_f32_e32 v51, 0xda24260, v53
	v_max_f32_e32 v52, 0xda24260, v56
	v_max_f32_e32 v54, 0xda24260, v54
	v_max_f32_e32 v53, 0xda24260, v57
	v_max_f32_e32 v55, 0xda24260, v55
	v_pk_mul_f32 v[46:47], v[46:47], v[52:53]
	v_pk_mul_f32 v[44:45], v[44:45], v[48:49]
	v_pk_mul_f32 v[48:49], v[42:43], v[54:55]
	v_pk_mul_f32 v[42:43], v[40:41], v[50:51]
	v_cvt_pk_bf16_f32 v40, v44, v45
	v_cvt_pk_bf16_f32 v41, v46, v47
	v_lshlrev_b64 v[50:51], 11, v[64:65]
	v_cvt_pk_bf16_f32 v42, v42, v43
	v_cvt_pk_bf16_f32 v43, v48, v49
	s_nop 0
	v_lshl_add_u64 v[50:51], s[6:7], 0, v[50:51]
	v_add_u32_e32 v48, 0xa0, v154
	v_lshl_add_u64 v[50:51], v[50:51], 0, v[152:153]
	v_ashrrev_i32_e32 v49, 31, v48
	global_store_dwordx4 v[50:51], v[40:43], off
	v_lshlrev_b64 v[52:53], 12, v[48:49]
	v_lshl_add_u64 v[52:53], s[4:5], 0, v[52:53]
	v_lshl_add_u64 v[52:53], v[52:53], 0, v[152:153]
	s_waitcnt vmcnt(15)
; #define PG8_BAR __builtin_amdgcn_s_barrier()
; __device__ __forceinline__ u32x4 pack8(f32x4 a, f32x4 b) { u32x4 w; w.x = cvt_pk_bf16(a[0], a[1]); w.y = cvt_pk_bf16(a[2], a[3]); w.z = cvt_pk_bf16(b[0], b[1]); w.w = cvt_pk_bf16(b[2], b[3]); return w; }
; #define EPI_LOOP(...) _Pragma("unroll") for (int ai = 0; ai < 2; ++ai) _Pragma("unroll") for (int m = 0; m < 4; ++m) { const int row = u.pm * 256 + ai * 128 + wr * 64 + m * 16 + fr; \
;     _Pragma("unroll") for (int bj = 0; bj < 2; ++bj) { const int tc = bj * 128 + wc * 32 + 8 * fq; f32x4 v0 = acc[ai][bj][m][0], v1 = acc[ai][bj][m][1]; __VA_ARGS__ } }
; template <class Epi>
; __device__ __forceinline__ void gemm_phase(LAS unsigned char* lds, const Gemm g, const StaticOrder& S, const Epi& E) {
;     ...
;         if (!has_next) break;
; #pragma unroll
;         for (int a = 0; a < 2; ++a)
; #pragma unroll
;             for (int b = 0; b < 2; ++b)
; #pragma unroll
;                 for (int m = 0; m < 4; ++m)
; #pragma unroll
;                     for (int n = 0; n < 2; ++n) acc[a][b][m][n] = (f32x4){0.f, 0.f, 0.f, 0.f};
;         cur = nxt; cA = nA; cB = nB; ++ui;
;         if (wr == 1) PG8_BAR;
;     }
;     __device__ __forceinline__ void operator()(const f32x4 (&acc)[2][2][4][2], const pg8::Unit& u, int wr, int wc, int fr, int fq) const {
;         EPI_LOOP({ const int col = u.pn * 256 + tc; f32x4 a0, a1; unpack_bf16x8(*(const u32x4*)(G + (size_t)row * 2048 + 1024 + col), a0, a1);
;                    _Pragma("unroll") for (int i = 0; i < 4; ++i) { a0[i] = fmaxf(a0[i], 1e-30f); a1[i] = fmaxf(a1[i], 1e-30f); }
;                    *(u32x4*)(MIXED + (size_t)row * D + col) = pack8(v0 * a0, v1 * a1); })
;     }
	v_lshlrev_b32_e32 v40, 16, v228
	v_and_b32_e32 v41, 0xffff0000, v228
	v_lshlrev_b32_e32 v42, 16, v229
	v_and_b32_e32 v43, 0xffff0000, v229
	v_lshlrev_b32_e32 v44, 16, v230
	v_and_b32_e32 v45, 0xffff0000, v230
	v_lshlrev_b32_e32 v46, 16, v231
	v_and_b32_e32 v47, 0xffff0000, v231
	v_max_f32_e32 v40, v40, v40
	v_max_f32_e32 v44, v44, v44
	v_max_f32_e32 v41, v41, v41
	v_max_f32_e32 v45, v45, v45
	v_max_f32_e32 v54, v42, v42
	v_max_f32_e32 v46, v46, v46
	v_max_f32_e32 v55, v43, v43
	v_max_f32_e32 v47, v47, v47
	v_max_f32_e32 v40, 0xda24260, v40
	v_max_f32_e32 v42, 0xda24260, v44
	v_max_f32_e32 v41, 0xda24260, v41
	v_max_f32_e32 v43, 0xda24260, v45
	v_max_f32_e32 v44, 0xda24260, v54
	v_max_f32_e32 v46, 0xda24260, v46
	v_max_f32_e32 v45, 0xda24260, v55
	v_max_f32_e32 v47, 0xda24260, v47
	v_pk_mul_f32 v[38:39], v[38:39], v[44:45]
	v_pk_mul_f32 v[36:37], v[36:37], v[40:41]
	v_pk_mul_f32 v[40:41], v[34:35], v[46:47]
	v_pk_mul_f32 v[34:35], v[32:33], v[42:43]
	v_cvt_pk_bf16_f32 v32, v36, v37
	v_cvt_pk_bf16_f32 v33, v38, v39
	s_nop 0
	v_cvt_pk_bf16_f32 v34, v34, v35
	v_cvt_pk_bf16_f32 v35, v40, v41
	s_nop 0
	s_nop 0
	global_store_dwordx4 v[50:51], v[32:35], off offset:256
	s_waitcnt vmcnt(15)
	s_nop 0
	v_lshlrev_b32_e32 v32, 16, v232
	v_and_b32_e32 v33, 0xffff0000, v232
	v_lshlrev_b32_e32 v34, 16, v233
	v_and_b32_e32 v35, 0xffff0000, v233
	v_lshlrev_b32_e32 v36, 16, v234
	v_and_b32_e32 v37, 0xffff0000, v234
	v_lshlrev_b32_e32 v38, 16, v235
	v_and_b32_e32 v39, 0xffff0000, v235
	v_max_f32_e32 v32, v32, v32
	v_max_f32_e32 v36, v36, v36
	v_max_f32_e32 v33, v33, v33
	v_max_f32_e32 v37, v37, v37
	v_max_f32_e32 v40, v34, v34
	v_max_f32_e32 v38, v38, v38
	v_max_f32_e32 v41, v35, v35
	v_max_f32_e32 v39, v39, v39
	v_max_f32_e32 v32, 0xda24260, v32
	v_max_f32_e32 v34, 0xda24260, v36
	v_max_f32_e32 v33, 0xda24260, v33
	v_max_f32_e32 v35, 0xda24260, v37
	v_max_f32_e32 v36, 0xda24260, v40
	v_max_f32_e32 v38, 0xda24260, v38
	v_max_f32_e32 v37, 0xda24260, v41
	v_max_f32_e32 v39, 0xda24260, v39
	v_pk_mul_f32 v[30:31], v[30:31], v[36:37]
	v_pk_mul_f32 v[28:29], v[28:29], v[32:33]
	v_pk_mul_f32 v[32:33], v[26:27], v[38:39]
	v_pk_mul_f32 v[26:27], v[24:25], v[34:35]
	v_cvt_pk_bf16_f32 v24, v28, v29
	v_cvt_pk_bf16_f32 v25, v30, v31
	v_lshlrev_b64 v[34:35], 11, v[48:49]
	v_cvt_pk_bf16_f32 v26, v26, v27
	v_cvt_pk_bf16_f32 v27, v32, v33
	s_nop 0
	v_lshl_add_u64 v[34:35], s[6:7], 0, v[34:35]
	v_add_u32_e32 v32, 0xb0, v154
	v_lshl_add_u64 v[34:35], v[34:35], 0, v[152:153]
	v_ashrrev_i32_e32 v33, 31, v32
	global_store_dwordx4 v[34:35], v[24:27], off
	v_lshlrev_b64 v[36:37], 12, v[32:33]
	v_lshl_add_u64 v[36:37], s[4:5], 0, v[36:37]
	v_lshl_add_u64 v[36:37], v[36:37], 0, v[152:153]
	s_waitcnt vmcnt(15)
	v_lshlrev_b32_e32 v24, 16, v236
	v_and_b32_e32 v25, 0xffff0000, v236
	v_lshlrev_b32_e32 v26, 16, v237
	v_and_b32_e32 v27, 0xffff0000, v237
	v_lshlrev_b32_e32 v28, 16, v238
	v_and_b32_e32 v29, 0xffff0000, v238
	v_lshlrev_b32_e32 v30, 16, v239
	v_and_b32_e32 v31, 0xffff0000, v239
	v_max_f32_e32 v24, v24, v24
	v_max_f32_e32 v28, v28, v28
	v_max_f32_e32 v25, v25, v25
	v_max_f32_e32 v29, v29, v29
	v_max_f32_e32 v38, v26, v26
	v_max_f32_e32 v30, v30, v30
	v_max_f32_e32 v39, v27, v27
	v_max_f32_e32 v31, v31, v31
	v_max_f32_e32 v24, 0xda24260, v24
	v_max_f32_e32 v26, 0xda24260, v28
	v_max_f32_e32 v25, 0xda24260, v25
	v_max_f32_e32 v27, 0xda24260, v29
	v_max_f32_e32 v28, 0xda24260, v38
	v_max_f32_e32 v30, 0xda24260, v30
	v_max_f32_e32 v29, 0xda24260, v39
	v_max_f32_e32 v31, 0xda24260, v31
	v_pk_mul_f32 v[22:23], v[22:23], v[28:29]
	v_pk_mul_f32 v[20:21], v[20:21], v[24:25]
	v_pk_mul_f32 v[24:25], v[18:19], v[30:31]
	v_pk_mul_f32 v[18:19], v[16:17], v[26:27]
	v_cvt_pk_bf16_f32 v16, v20, v21
	v_cvt_pk_bf16_f32 v17, v22, v23
	s_nop 0
	v_cvt_pk_bf16_f32 v18, v18, v19
	v_cvt_pk_bf16_f32 v19, v24, v25
	s_nop 0
	s_nop 0
	global_store_dwordx4 v[34:35], v[16:19], off offset:256
	s_waitcnt vmcnt(15)
	s_nop 0
	v_lshlrev_b32_e32 v16, 16, v240
	v_and_b32_e32 v17, 0xffff0000, v240
	v_lshlrev_b32_e32 v18, 16, v241
	v_and_b32_e32 v19, 0xffff0000, v241
	v_lshlrev_b32_e32 v20, 16, v242
	v_and_b32_e32 v21, 0xffff0000, v242
	v_lshlrev_b32_e32 v22, 16, v243
	v_and_b32_e32 v23, 0xffff0000, v243
	v_max_f32_e32 v16, v16, v16
	v_max_f32_e32 v20, v20, v20
	v_max_f32_e32 v17, v17, v17
	v_max_f32_e32 v21, v21, v21
	v_max_f32_e32 v24, v18, v18
	v_max_f32_e32 v22, v22, v22
	v_max_f32_e32 v25, v19, v19
	v_max_f32_e32 v23, v23, v23
	v_max_f32_e32 v16, 0xda24260, v16
	v_max_f32_e32 v18, 0xda24260, v20
	v_max_f32_e32 v17, 0xda24260, v17
	v_max_f32_e32 v19, 0xda24260, v21
	v_max_f32_e32 v20, 0xda24260, v24
	v_max_f32_e32 v22, 0xda24260, v22
	v_max_f32_e32 v21, 0xda24260, v25
	v_max_f32_e32 v23, 0xda24260, v23
	v_pk_mul_f32 v[14:15], v[14:15], v[20:21]
	v_pk_mul_f32 v[12:13], v[12:13], v[16:17]
	v_pk_mul_f32 v[16:17], v[10:11], v[22:23]
	v_pk_mul_f32 v[10:11], v[8:9], v[18:19]
	v_cvt_pk_bf16_f32 v8, v12, v13
	v_cvt_pk_bf16_f32 v9, v14, v15
	s_nop 0
	v_cvt_pk_bf16_f32 v10, v10, v11
	v_cvt_pk_bf16_f32 v11, v16, v17
	s_nop 0
	v_lshlrev_b64 v[16:17], 11, v[32:33]
	v_lshl_add_u64 v[16:17], s[6:7], 0, v[16:17]
	v_lshl_add_u64 v[16:17], v[16:17], 0, v[152:153]
	global_store_dwordx4 v[16:17], v[8:11], off
	s_waitcnt vmcnt(15)
	s_nop 0
	v_lshlrev_b32_e32 v8, 16, v244
	v_and_b32_e32 v9, 0xffff0000, v244
	v_lshlrev_b32_e32 v10, 16, v245
	v_and_b32_e32 v11, 0xffff0000, v245
	v_lshlrev_b32_e32 v12, 16, v246
	v_and_b32_e32 v13, 0xffff0000, v246
	v_lshlrev_b32_e32 v14, 16, v247
	v_and_b32_e32 v15, 0xffff0000, v247
	v_max_f32_e32 v8, v8, v8
	v_max_f32_e32 v12, v12, v12
	v_max_f32_e32 v9, v9, v9
	v_max_f32_e32 v13, v13, v13
	v_max_f32_e32 v14, v14, v14
	v_max_f32_e32 v15, v15, v15
	v_max_f32_e32 v18, v10, v10
	v_max_f32_e32 v19, v11, v11
	v_max_f32_e32 v8, 0xda24260, v8
	v_max_f32_e32 v10, 0xda24260, v12
	v_max_f32_e32 v9, 0xda24260, v9
	v_max_f32_e32 v11, 0xda24260, v13
	v_max_f32_e32 v14, 0xda24260, v14
	v_max_f32_e32 v15, 0xda24260, v15
	v_max_f32_e32 v12, 0xda24260, v18
	v_max_f32_e32 v13, 0xda24260, v19
	v_pk_mul_f32 v[4:5], v[4:5], v[8:9]
	v_pk_mul_f32 v[8:9], v[2:3], v[14:15]
	v_pk_mul_f32 v[2:3], v[0:1], v[10:11]
	v_pk_mul_f32 v[6:7], v[6:7], v[12:13]
	v_cvt_pk_bf16_f32 v0, v4, v5
	s_nop 0
	v_cvt_pk_bf16_f32 v1, v6, v7
	v_cvt_pk_bf16_f32 v2, v2, v3
	v_cvt_pk_bf16_f32 v3, v8, v9
	global_store_dwordx4 v[16:17], v[0:3], off offset:256
	s_cbranch_vccnz .LBB0_662
	s_andn2_b64 vcc, exec, s[0:1]
	s_cbranch_vccnz .LBB0_661
	s_barrier
	s_branch .LBB0_661
